# byte-phase pin: never-executed 4-byte pad ahead of the FFN-up GEMM loop puts its K-loop head back at 0 mod 8
# speedup vs baseline: 1.0036x; 1.0036x over previous
; __device__ __forceinline__ int otid() { int t = threadIdx.x; asm volatile("" : "+v"(t)); return t; }
; #define PG8_STAGE(bufoff, gbase, voff) do { _Pragma("unroll") for (int _i = 0; _i < 2; ++_i) \
;         __builtin_amdgcn_global_load_lds((const unsigned*)((const char*)(gbase) + (voff)[_i]), (PG8_LAS unsigned*)(lds + (bufoff) + ldsw + _i * 8192), 16, 0, 0); } while (0)
; template <class Epi, class Sched, bool ALIGN_EPI = false, bool SP2 = false>
; __device__ __forceinline__ void gemm_phase(PG8_LAS unsigned char* lds, const Gemm g, const Sched& S, const Epi& E) {
;     const int tid = otid(), wid = __builtin_amdgcn_readfirstlane(tid >> 6), lane = tid & 63, wr = wid >> 2, wc = wid & 3, fr = lane & 15, fq = lane >> 4;
;     const int K = g.K, nt = K / BK;
;     unsigned voffA[2], voffB[2];
; #pragma unroll
;     for (int i = 0; i < 2; ++i) { int R, C; stage_rc(tid * 16 + i * 8192, R, C); const int Rb = Epi::PERM ? ((R & ~31) + perm32(R & 31)) : R;
;         voffA[i] = (unsigned)(R * K + C) * 2u; voffB[i] = (unsigned)(Rb * K + C) * 2u; }
;     const size_t kstep = (size_t)(BK * 2);
;     const size_t hstep = (size_t)HALF * K * 2;
;     const size_t tstep = 2 * hstep;
;     const unsigned ldsw = (unsigned)wid * 1024u;
;     const int aoff = lds_byte(wr * 64 + fr, fq * 8), boff = lds_byte(wc * 32 + fr, fq * 8);
;     ...
;     const char* cA = (const char*)g.A + (size_t)cur.pm * tstep; const char* cB = (const char*)g.Bt + (size_t)cur.pn * tstep;
;     S.a_ready(cur);
;     if constexpr (SP2) {
;         PG8_STAGE(PG8_SB(0, 0), cB, voffB); PG8_STAGE(PG8_SB(0, 1), cB + hstep, voffB); PG8_STAGE(PG8_SA(0, 0), cA, voffA); PG8_STAGE(PG8_SA(0, 1), cA + hstep, voffA);
;         if (wr == 1) PG8_BAR;
;         PG8_WAIT_V(2); PG8_BAR;
;         PG8_STAGE(PG8_SB(1, 0), cB + kstep, voffB); PG8_STAGE(PG8_SA(1, 0), cA + kstep, voffA); PG8_STAGE(PG8_SB(1, 1), cB + hstep + kstep, voffB);
;         PG8_WAIT_V(6); PG8_BAR;
;     } else {
;         PG8_STAGE(PG8_SB(0, 0), cB, voffB); PG8_STAGE(PG8_SA(0, 0), cA, voffA); PG8_STAGE(PG8_SB(0, 1), cB + hstep, voffB); PG8_STAGE(PG8_SA(0, 1), cA + hstep, voffA);
;         if (wr == 1) PG8_BAR;
;         PG8_WAIT_V(4); PG8_BAR;
;         PG8_STAGE(PG8_SB(1, 0), cB + kstep, voffB); PG8_STAGE(PG8_SA(1, 0), cA + kstep, voffA); PG8_STAGE(PG8_SB(1, 1), cB + hstep + kstep, voffB);
;         PG8_WAIT_V(6); PG8_BAR;
;     }
.LBB0_867:
	v_lshrrev_b32_e32 v18, 1, v8
	v_and_b32_e32 v18, 24, v18
	v_and_b32_e32 v9, 15, v8
	v_lshlrev_b32_e32 v19, 1, v18
	v_lshlrev_b32_e32 v8, 2, v8
	s_sext_i32_i16 s13, s14
	v_lshl_or_b32 v142, s30, 6, v9
	v_lshl_or_b32 v9, v9, 6, v19
	s_lshl_b32 s14, s30, 13
	v_and_b32_e32 v8, 32, v8
	v_bitop3_b32 v143, v9, s14, v8 bitop3:0xde
	s_lshl_b32 s14, s27, 5
	s_and_b32 s38, s14, 0x60
	s_lshl_b32 s14, s38, 7
	v_lshl_add_u64 v[10:11], s[6:7], 0, v[0:1]
	v_mov_b32_e32 v131, v1
	v_bitop3_b32 v144, v9, s14, v8 bitop3:0xde
	s_add_i32 s14, s18, 0x18000
	v_lshl_add_u64 v[12:13], s[6:7], 0, v[130:131]
	v_mov_b32_e32 v135, v1
	v_lshl_add_u64 v[8:9], v[10:11], 0, s[34:35]
	s_mov_b32 m0, s14
	s_add_i32 s59, s18, 0x1a000
	v_lshl_add_u64 v[14:15], s[48:49], 0, v[134:135]
	v_mov_b32_e32 v133, v1
	s_waitcnt vmcnt(2)
	s_barrier
	global_load_lds_dwordx4 v[8:9], off
	v_lshl_add_u64 v[8:9], v[12:13], 0, s[34:35]
	s_mov_b32 m0, s59
	s_add_i32 s60, s18, 0x8000
	s_add_i32 s61, s18, 0xa000
	v_lshl_add_u64 v[16:17], s[48:49], 0, v[132:133]
	global_load_lds_dwordx4 v[8:9], off
	v_lshl_add_u64 v[8:9], v[14:15], 0, s[34:35]
	s_mov_b32 m0, s60
	s_add_u32 s30, s6, 0x40080
	global_load_lds_dwordx4 v[8:9], off
	v_lshl_add_u64 v[8:9], v[16:17], 0, s[34:35]
	s_mov_b32 m0, s61
	s_addc_u32 s31, s7, 0
	s_add_i32 s62, s18, 0x1c000
	global_load_lds_dwordx4 v[8:9], off
	v_lshl_add_u64 v[8:9], s[30:31], 0, v[0:1]
	s_mov_b32 m0, s62
	s_add_i32 s63, s18, 0x1e000
	global_load_lds_dwordx4 v[8:9], off
	v_lshl_add_u64 v[8:9], s[30:31], 0, v[130:131]
	s_mov_b32 m0, s63
	s_cmpk_lt_u32 s26, 0x100
	global_load_lds_dwordx4 v[8:9], off
	v_lshlrev_b32_e32 v8, 14, v6
	v_and_b32_e32 v8, 0xffff8000, v8
	v_lshl_add_u32 v5, v5, 11, v8
	v_and_b32_e32 v6, 1, v6
	v_lshl_or_b32 v5, v6, 6, v5
	v_lshl_add_u32 v136, v7, 1, v5
	v_lshlrev_b32_e32 v5, 14, v2
	v_and_b32_e32 v5, 0xffff8000, v5
	s_waitcnt vmcnt(6)
	v_lshl_add_u32 v3, v3, 11, v5
	v_and_b32_e32 v2, 1, v2
	v_lshl_or_b32 v2, v2, 6, v3
	s_cselect_b64 s[26:27], -1, 0
	v_or_b32_e32 v145, s38, v18
	v_mov_b32_e32 v137, v1
	v_lshl_add_u32 v138, v4, 1, v2
	v_mov_b32_e32 v139, v1
	s_mov_b32 s64, 0
	s_barrier
	s_branch .LBB0_870
	s_nop 0
